# P1 tile order v3: block permutation re-optimised with fitted tile costs; the 16 mem-tile WGs stop after round 4 and their round-5 tiles are done in round 6 by idle WGs of the same XCD
# baseline (speedup 1.0000x reference)
.Lp1r1:
	s_mov_b32 s98, 0x3d07a5
	s_cmp_eq_u32 s99, 1
	s_cmov_b32 s98, 0xa9cdc8
	s_cmp_eq_u32 s99, 2
	s_cmov_b32 s98, 0x429f9c
	s_cmp_eq_u32 s99, 3
	s_cmov_b32 s98, 0x80df93
	s_cmp_eq_u32 s99, 4
	s_cmov_b32 s98, 0xc9c179
	s_cmp_eq_u32 s99, 5
	s_cmov_b32 s98, 0x80eeea
	s_cmp_eq_u32 s99, 6
	s_cmov_b32 s98, 0x9c8cea
	s_cmp_eq_u32 s99, 7
	s_cmov_b32 s98, 0xccfaa
	s_branch .Lp1rdone
.Lp1r2:
	s_mov_b32 s98, 0x2d6bc4
	s_cmp_eq_u32 s99, 1
	s_cmov_b32 s98, 0xf18b8a
	s_cmp_eq_u32 s99, 2
	s_cmov_b32 s98, 0xe0dd13
	s_cmp_eq_u32 s99, 3
	s_cmov_b32 s98, 0x222bf3
	s_cmp_eq_u32 s99, 4
	s_cmov_b32 s98, 0xec5f1
	s_cmp_eq_u32 s99, 5
	s_cmov_b32 s98, 0x5dcc0d
	s_cmp_eq_u32 s99, 6
	s_cmov_b32 s98, 0x41d9f1
	s_cmp_eq_u32 s99, 7
	s_cmov_b32 s98, 0x853d47
	s_branch .Lp1rdone
.Lp1r3:
	s_mov_b32 s98, 0x843faa
	s_cmp_eq_u32 s99, 1
	s_cmov_b32 s98, 0xcef444
	s_cmp_eq_u32 s99, 2
	s_cmov_b32 s98, 0x7d4c0d
	s_cmp_eq_u32 s99, 3
	s_cmov_b32 s98, 0x629eb4
	s_cmp_eq_u32 s99, 4
	s_cmov_b32 s98, 0xa3e899
	s_cmp_eq_u32 s99, 5
	s_cmov_b32 s98, 0xd2f60a
	s_cmp_eq_u32 s99, 6
	s_cmov_b32 s98, 0x473a27
	s_cmp_eq_u32 s99, 7
	s_cmov_b32 s98, 0x83545f
	s_branch .Lp1rdone
.Lp1r4:
	s_mov_b32 s98, 0xe9d384
	s_cmp_eq_u32 s99, 1
	s_cmov_b32 s98, 0xa3ac63
	s_cmp_eq_u32 s99, 2
	s_cmov_b32 s98, 0x4ceb07
	s_cmp_eq_u32 s99, 3
	s_cmov_b32 s98, 0xf90b0b
	s_cmp_eq_u32 s99, 4
	s_cmov_b32 s98, 0xe84d59
	s_cmp_eq_u32 s99, 5
	s_cmov_b32 s98, 0x7caf2
	s_cmp_eq_u32 s99, 6
	s_cmov_b32 s98, 0xf7aa1
	s_cmp_eq_u32 s99, 7
	s_cmov_b32 s98, 0xeae621
	s_branch .Lp1rdone
.Lp1r5:
	s_mov_b32 s98, 0xeee501
	s_cmp_eq_u32 s99, 1
	s_cmov_b32 s98, 0xd0d7c2
	s_cmp_eq_u32 s99, 2
	s_cmov_b32 s98, 0x88ee1d
	s_cmp_eq_u32 s99, 3
	s_cmov_b32 s98, 0x66e1e2
	s_cmp_eq_u32 s99, 4
	s_cmov_b32 s98, 0x501777
	s_cmp_eq_u32 s99, 5
	s_cmov_b32 s98, 0x2a87e6
	s_cmp_eq_u32 s99, 6
	s_cmov_b32 s98, 0x3eb1a2
	s_cmp_eq_u32 s99, 7
	s_cmov_b32 s98, 0xc45f13
	s_branch .Lp1rdone
.Lp1r6:
	s_mov_b32 s98, 0xbf0519
	s_cmp_eq_u32 s99, 1
	s_cmov_b32 s98, 0xa444f7
	s_cmp_eq_u32 s99, 2
	s_cmov_b32 s98, 0xbb9113
	s_cmp_eq_u32 s99, 3
	s_cmov_b32 s98, 0xddaa0c
	s_cmp_eq_u32 s99, 4
	s_cmov_b32 s98, 0xcbd2e0
	s_cmp_eq_u32 s99, 5
	s_cmov_b32 s98, 0xf2e213
	s_cmp_eq_u32 s99, 6
	s_cmov_b32 s98, 0xa34e5a
	s_cmp_eq_u32 s99, 7
	s_cmov_b32 s98, 0xab78c8
.Lp1rdone:
	s_lshr_b32 s100, s2, 3
	s_lshr_b32 s101, s100, 2
	s_mul_i32 s101, s101, 3
	s_lshr_b32 s98, s98, s101
	s_and_b32 s98, s98, 7
	s_lshl_b32 s98, s98, 2
	s_and_b32 s100, s100, 3
	s_or_b32 s98, s98, s100
	s_lshl_b32 s98, s98, 3
	s_or_b32 s98, s98, s99
	s_mul_i32 s10, s71, s97
	s_mul_hi_u32 s11, s71, s96
	s_add_i32 s11, s11, s10
	s_mul_i32 s10, s71, s96
	s_add_u32 s10, s10, s98
	s_addc_u32 s11, s11, s3
	s_cmp_lt_u32 s71, 5
	s_cbranch_scc1 .Lp1sp_done
	s_cmp_lt_u32 s2, 0xf0
	s_cbranch_scc1 .Lp1sp_nomem
	s_mov_b32 s10, 0x100000
	s_mov_b32 s11, 0
	s_branch .Lp1sp_done
.Lp1sp_nomem:
	s_cmp_lg_u32 s71, 6
	s_cbranch_scc1 .Lp1sp_done
	s_sub_u32 s100, s98, 0x9a
	s_cmp_gt_u32 s100, 15
	s_cbranch_scc1 .Lp1sp_done
	s_lshr_b32 s100, s100, 3
	s_mov_b32 s101, 0xeee501
	s_cmp_eq_u32 s99, 1
	s_cmov_b32 s101, 0xd0d7c2
	s_cmp_eq_u32 s99, 2
	s_cmov_b32 s101, 0x88ee1d
	s_cmp_eq_u32 s99, 3
	s_cmov_b32 s101, 0x66e1e2
	s_cmp_eq_u32 s99, 4
	s_cmov_b32 s101, 0x501777
	s_cmp_eq_u32 s99, 5
	s_cmov_b32 s101, 0x2a87e6
	s_cmp_eq_u32 s99, 6
	s_cmov_b32 s101, 0x3eb1a2
	s_cmp_eq_u32 s99, 7
	s_cmov_b32 s101, 0xc45f13
	s_lshr_b32 s101, s101, 21
	s_lshl_b32 s101, s101, 2
	s_or_b32 s101, s101, 2
	s_or_b32 s101, s101, s100
	s_lshl_b32 s101, s101, 3
	s_or_b32 s101, s101, s99
	s_add_u32 s10, s101, 0x500
	s_mov_b32 s11, 0
.Lp1sp_done:
	v_cmp_gt_i64_e32 vcc, s[10:11], v[162:163]
	v_cmp_lt_i64_e64 s[38:39], s[10:11], v[160:161]
	s_cbranch_vccnz .LBB0_149
	s_ashr_i32 s11, s10, 31
	s_lshr_b32 s11, s11, 29
	s_add_i32 s20, s10, s11
	s_and_b32 s11, s20, -8
	s_sub_i32 s21, s10, s11
	s_cmp_gt_i32 s21, 1
	s_mov_b64 s[10:11], -1
	s_cbranch_scc0 .LBB0_146
	s_mul_i32 s10, s21, 0xd3
	s_add_i32 s22, s10, 2
	s_mov_b64 s[10:11], 0
